# initial cooperative-groups grid sync replaced by the XCD-hierarchical barrier (cloned), placed after the loop preheader
# speedup vs baseline: 1.0080x; 1.0008x over previous
; DI int fresh_lane() { int l_; asm volatile("v_mbcnt_lo_u32_b32 %0, -1, 0\n\tv_mbcnt_hi_u32_b32 %0, -1, %0" : "=v"(l_)); return l_; }
; #define GSYNC() do { xcd_barrier(xbar, wave_s * 64 + fresh_lane()); xcd_barrier(xbar, wave_s * 64 + fresh_lane()); } while (0)
; #define GSYNC() xcd_barrier(xbar, wave_s * 64 + fresh_lane())
; __global__ void __launch_bounds__(512, 2) fwd_kernel(Args args) {
;     ...
;     grid.sync();
;     for (int l = 0; l < 2; ++l) {
;         const bool need_ctx = (l == 0);
;         const int Mres = need_ctx ? MTOT : NLAT;
;         norm_phase(args, wave_s, l, 1, MTOT);
;     ...
;         norm_phase(args, wave_s, l, 1, MTOT);
;     ...
;         GSYNC();
;         { pg8::Gemm g{(const bf16*)(args.ws + WS_H), (const bf16*)(args.ws + WS_WIN) + (size_t)l * 3072 * 1024, MTOT, INW, 1024}; pg8::StaticOrder S; S.init(MTOT, INW, G, bx);
;           pg8::EpiBf16 E{(bf16*)(args.ws + WS_P), INW}; pg8::gemm_phase<pg8::EpiBf16, pg8::StaticOrder, true, true>(lds, g, S, E, wave_s * 64 + fresh_lane());
;     ...
;           pg8::gemm_phase<pg8::EpiBf16, pg8::StaticOrder, true, true>(lds, g, S, E, wave_s * 64 + fresh_lane());
;     ...
;           if (l == 0 && bx >= (1584 % G)) p0_transposes(args, wave_s, lds, 1536, 12544, (bx - 1584 % G) * 8 + wave_s, (G - 1584 % G) * 8);
.LBB0_42:
	v_lshrrev_b32_e32 v2, 20, v0
	v_lshrrev_b32_e32 v0, 10, v0
	v_or_b32_e32 v0, v0, v2
	s_movk_i32 s0, 0x3ff
	v_and_or_b32 v0, v0, s0, v1
	v_cmp_eq_u32_e32 vcc, 0, v0
	s_waitcnt lgkmcnt(0)
	s_barrier
	s_and_saveexec_b64 s[0:1], vcc
	s_branch .LBB0_52
.LBB0_52:
	v_writelane_b32 v252, s44, 34
	s_nop 1
	v_writelane_b32 v252, s45, 35
	v_writelane_b32 v252, s46, 36
	v_writelane_b32 v252, s47, 37
	v_writelane_b32 v252, s48, 38
	v_writelane_b32 v252, s49, 39
	v_writelane_b32 v252, s50, 40
	v_writelane_b32 v252, s51, 41
	v_writelane_b32 v252, s52, 42
	v_writelane_b32 v252, s53, 43
	v_writelane_b32 v252, s54, 44
	v_writelane_b32 v252, s55, 45
	v_writelane_b32 v252, s56, 46
	v_writelane_b32 v252, s57, 47
	v_writelane_b32 v252, s58, 48
	v_writelane_b32 v252, s59, 49
	s_or_b64 exec, exec, s[0:1]
	s_add_u32 s0, s88, 0xe00000
	v_writelane_b32 v252, s0, 50
	s_addc_u32 s0, s89, 0
	v_writelane_b32 v252, s0, 51
	s_add_u32 s0, s88, 0x1200000
	v_writelane_b32 v252, s0, 52
	s_addc_u32 s0, s89, 0
	v_writelane_b32 v252, s0, 53
	s_add_u32 s0, s88, 0x2800000
	v_writelane_b32 v252, s0, 54
	s_addc_u32 s0, s89, 0
	s_add_u32 s12, s88, 0x3800000
	v_writelane_b32 v252, s0, 55
	s_addc_u32 s13, s89, 0
	s_lshl_b32 s0, s65, 4
	s_lshl_b32 s1, s16, 1
	s_lshl_b32 s14, s90, 4
	s_add_i32 s18, s1, s0
	s_cmp_lt_i32 s18, 0x8400
	s_cselect_b64 s[4:5], -1, 0
	s_add_u32 s74, s88, 0x3400000
	s_addc_u32 s75, s89, 0
	s_add_u32 s36, s88, 0x1200
	s_addc_u32 s37, s89, 0
	s_add_u32 s38, s88, 0x1400
	s_addc_u32 s39, s89, 0
	s_add_u32 s40, s88, 0x1500
	s_addc_u32 s41, s89, 0
	s_add_u32 s46, s88, 0x1600
	s_addc_u32 s47, s89, 0
	s_add_u32 s20, s88, 0x1700
	s_addc_u32 s21, s89, 0
	s_add_u32 s22, s88, 0x1800
	s_addc_u32 s23, s89, 0
	s_add_u32 s24, s88, 0x1900
	s_addc_u32 s25, s89, 0
	s_add_u32 s26, s88, 0x1a00
	s_addc_u32 s27, s89, 0
	s_add_u32 s34, s88, 0x1b00
	s_addc_u32 s35, s89, 0
	s_add_u32 s30, s88, 0x1c00
	v_writelane_b32 v252, s4, 56
	s_addc_u32 s31, s89, 0
	s_mov_b32 s33, 0x8000
	v_writelane_b32 v252, s5, 57
	s_add_u32 s4, s88, 0x1d00
	s_addc_u32 s5, s89, 0
	v_writelane_b32 v252, s4, 58
	s_mov_b32 s97, 0
	v_writelane_b32 v255, s94, 0
	v_writelane_b32 v252, s5, 59
	s_add_u32 s4, s88, 0x1e00
	s_addc_u32 s5, s89, 0
	v_writelane_b32 v252, s4, 60
	v_writelane_b32 v255, s74, 1
	v_writelane_b32 v255, s75, 2
	v_writelane_b32 v252, s5, 61
	s_add_u32 s4, s88, 0x1f00
	s_addc_u32 s5, s89, 0
	v_writelane_b32 v252, s4, 62
	v_writelane_b32 v255, s36, 3
	v_mov_b32_e32 v161, 0
	v_writelane_b32 v252, s5, 63
	s_add_u32 s4, s88, 0x2000
	s_addc_u32 s5, s89, 0
	v_writelane_b32 v253, s4, 0
	v_writelane_b32 v255, s37, 4
	v_writelane_b32 v255, s38, 5
	v_writelane_b32 v253, s5, 1
	s_add_u32 s4, s88, 0x2100
	s_addc_u32 s5, s89, 0
	v_writelane_b32 v253, s4, 2
	v_writelane_b32 v255, s39, 6
	v_writelane_b32 v255, s40, 7
	v_writelane_b32 v253, s5, 3
	s_add_u32 s4, s88, 0x2200
	s_addc_u32 s5, s89, 0
	v_writelane_b32 v253, s4, 4
	v_readlane_b32 s48, v252, 1
	v_writelane_b32 v255, s41, 8
	v_writelane_b32 v253, s5, 5
	s_add_u32 s4, s88, 0x2300
	s_addc_u32 s5, s89, 0
	v_writelane_b32 v253, s4, 6
	v_readlane_b32 s49, v252, 2
	v_writelane_b32 v255, s46, 9
	v_writelane_b32 v253, s5, 7
	s_add_u32 s4, s88, 0x4400
	s_addc_u32 s5, s89, 0
	v_writelane_b32 v253, s4, 8
	s_mov_b64 s[48:49], s[20:21]
	v_writelane_b32 v255, s47, 10
	v_writelane_b32 v253, s5, 9
	s_add_u32 s4, s88, 0x4500
	s_addc_u32 s5, s89, 0
	s_add_u32 s84, s88, 0xbc00000
	s_addc_u32 s85, s89, 0
	v_writelane_b32 v253, s4, 10
	s_cmpk_lt_i32 s65, 0x630
	v_readlane_b32 s50, v252, 3
	v_writelane_b32 v253, s5, 11
	s_cselect_b64 s[4:5], -1, 0
	s_ashr_i32 s83, s65, 31
	s_lshr_b32 s0, s83, 29
	s_add_i32 s0, s65, s0
	v_writelane_b32 v253, s4, 12
	s_ashr_i32 s8, s0, 3
	s_and_b32 s0, s0, -8
	v_writelane_b32 v253, s5, 13
	s_sub_i32 s11, s65, s0
	s_ashr_i32 s0, s90, 31
	v_writelane_b32 v253, s0, 14
	s_add_i32 s0, s10, 0
	s_add_u32 s4, s88, 0x140000
	v_writelane_b32 v253, s0, 15
	s_addc_u32 s5, s89, 0
	v_writelane_b32 v253, s4, 16
	v_readlane_b32 s10, v252, 33
	v_readlane_b32 s51, v252, 4
	v_writelane_b32 v253, s5, 17
	s_add_u32 s4, s88, 0x142000
	s_addc_u32 s5, s89, 0
	v_writelane_b32 v253, s4, 18
	v_writelane_b32 v255, s48, 11
	s_mov_b64 s[50:51], s[22:23]
	v_writelane_b32 v253, s5, 19
	s_add_u32 s4, s88, 0x144000
	s_addc_u32 s5, s89, 0
	v_writelane_b32 v253, s4, 20
	v_writelane_b32 v255, s49, 12
	v_readlane_b32 s52, v252, 5
	v_writelane_b32 v253, s5, 21
	s_add_u32 s4, s88, 0x145000
	s_addc_u32 s5, s89, 0
	v_writelane_b32 v253, s4, 22
	s_cmp_lt_i32 s10, 0x8400
	v_readlane_b32 s53, v252, 6
	v_writelane_b32 v253, s5, 23
	s_cselect_b64 s[4:5], -1, 0
	v_writelane_b32 v253, s4, 24
	v_writelane_b32 v255, s50, 13
	s_mov_b64 s[52:53], s[24:25]
	v_writelane_b32 v253, s5, 25
	s_add_u32 s4, s88, 0x18200000
	s_addc_u32 s5, s89, 0
	v_writelane_b32 v253, s4, 26
	s_cmpk_lt_i32 s65, 0x840
	v_writelane_b32 v255, s51, 14
	v_writelane_b32 v253, s5, 27
	s_cselect_b64 s[4:5], -1, 0
	v_writelane_b32 v253, s4, 28
	s_and_b32 s0, s1, 6
	s_lshr_b32 s6, s2, 8
	v_writelane_b32 v253, s5, 29
	v_writelane_b32 v253, s0, 30
	s_mul_i32 s0, s6, 0xb400
	s_add_i32 s9, s0, 0
	s_add_u32 s0, s88, 0x1c400000
	s_addc_u32 s1, s89, 0
	v_writelane_b32 v253, s0, 31
	v_readlane_b32 s54, v252, 7
	v_readlane_b32 s55, v252, 8
	v_writelane_b32 v253, s1, 32
	s_mul_hi_i32 s0, s65, 0x3e0f83e1
	s_lshr_b32 s1, s0, 31
	s_ashr_i32 s0, s0, 5
	s_add_i32 s0, s0, s1
	s_mul_i32 s1, s0, 0x84
	s_sub_i32 s1, s65, s1
	s_ashr_i32 s4, s0, 2
	s_lshl_b32 s5, s1, 6
	s_cmp_lt_i32 s1, 4
	s_cselect_b32 s1, 8, 13
	s_cselect_b32 s7, s33, 0xffffff00
	s_lshl_b32 s1, s4, s1
	s_add_i32 s4, s7, s5
	s_lshl_b32 s0, s0, 6
	s_add_i32 s7, s4, s1
;     __host__ __device__ bool next(int i, Unit& u) const {
;         const long L = (long)i * G + c; if (L >= nwg) return false;
;         int wgid = (int)L; { const int q = nwg / NXCD, r = nwg % NXCD, xcd = wgid % NXCD, off = wgid / NXCD; wgid = (xcd < r ? xcd * (q + 1) : r * (q + 1) + (xcd - r) * q) + off; }
;         const int nig = WGM * nN, gid = wgid / nig, fm = gid * WGM, gsz = (nM - fm) < WGM ? (nM - fm) : WGM;
;         u.pm = fm + ((wgid % nig) % gsz); u.pn = (wgid % nig) / gsz; return true;
; template <class Epi, class Sched, bool ALIGN_EPI = false, bool SP2 = false>
; __device__ __forceinline__ void gemm_phase(PG8_LAS unsigned char* lds, const Gemm g, const Sched& S, const Epi& E, int tid_in) {
;     ...
;     const char* cA = (const char*)g.A + (size_t)cur.pm * tstep; const char* cB = (const char*)g.Bt + (size_t)cur.pn * tstep;
	s_and_b32 s15, s0, 0xc0
	s_cmpk_lt_u32 s2, 0x100
	s_cselect_b64 s[0:1], -1, 0
	s_and_b64 s[4:5], s[0:1], exec
	s_movk_i32 s4, 0x400
	s_cselect_b32 s5, s4, 0x600
	s_movk_i32 s4, 0x300
	s_cselect_b32 s4, s4, 0x500
	v_writelane_b32 v253, s4, 33
	s_lshl_b32 s4, s16, 2
	s_and_b32 s4, s4, 0xffffff0
	v_writelane_b32 v253, s4, 34
	s_and_b32 s4, s2, 0xffffff00
	s_add_i32 s4, s4, 0x11800
	v_writelane_b32 v253, s4, 35
	s_lshl_b32 s4, s6, 11
	s_add_i32 s4, s4, 0
	s_add_i32 s4, s4, 0x20000
	v_writelane_b32 v253, s4, 36
	s_lshl_b32 s4, s16, 4
	s_and_b32 s17, s4, 32
	s_lshl_b32 s4, s65, 9
	s_add_i32 s4, s94, s4
	v_writelane_b32 v253, s4, 37
	v_writelane_b32 v253, s15, 38
	v_writelane_b32 v253, s5, 39
	s_or_b32 s4, s15, s5
	v_writelane_b32 v253, s4, 40
	v_writelane_b32 v253, s7, 41
	s_or_b32 s4, s7, 63
	v_writelane_b32 v253, s4, 42
	s_lshl_b32 s4, s16, 5
	v_writelane_b32 v253, s4, 43
	s_and_b32 s28, s4, 32
	s_lshl_b32 s4, s17, 6
	v_writelane_b32 v253, s17, 44
	s_or_b32 s5, s4, 64
	v_writelane_b32 v253, s5, 45
	s_or_b32 s5, s4, 0x80
	v_writelane_b32 v253, s5, 46
	s_or_b32 s5, s4, 0xc0
	v_writelane_b32 v253, s5, 47
	s_or_b32 s5, s4, 0x200
	v_writelane_b32 v253, s5, 48
	s_or_b32 s5, s4, 0x240
	v_writelane_b32 v253, s5, 49
	s_or_b32 s5, s4, 0x280
	v_writelane_b32 v253, s5, 50
	s_or_b32 s5, s4, 0x2c0
	v_writelane_b32 v253, s5, 51
	s_or_b32 s5, s4, 0x400
	v_writelane_b32 v253, s5, 52
	s_or_b32 s5, s4, 0x440
	v_writelane_b32 v253, s5, 53
	s_or_b32 s5, s4, 0x480
	v_writelane_b32 v253, s5, 54
	s_or_b32 s5, s4, 0x4c0
	v_writelane_b32 v253, s5, 55
	s_or_b32 s5, s4, 0x600
	v_writelane_b32 v253, s5, 56
	s_or_b32 s5, s4, 0x640
	v_writelane_b32 v253, s5, 57
	s_or_b32 s5, s4, 0x680
	v_writelane_b32 v253, s5, 58
	v_writelane_b32 v253, s4, 59
	s_or_b32 s4, s4, 0x6c0
	v_writelane_b32 v253, s4, 60
	s_lshl_b32 s4, s90, 9
	v_writelane_b32 v253, s4, 61
	s_add_u32 s4, s88, 0x7a00000
	s_addc_u32 s5, s89, 0
	v_writelane_b32 v253, s4, 62
	v_writelane_b32 v255, s52, 15
	s_mov_b64 s[54:55], s[26:27]
	v_writelane_b32 v253, s5, 63
	s_lshl_b32 s4, s6, 6
	v_writelane_b32 v254, s4, 0
	s_bfe_u32 s4, s2, 0x10006
	s_lshl_b32 s5, s4, 6
	s_lshl_b32 s6, s4, 5
	s_lshl_b32 s4, s4, 7
	s_add_i32 s4, s4, 0
	v_writelane_b32 v254, s6, 1
	s_add_i32 s4, s4, 0x16800
	v_writelane_b32 v254, s4, 2
	s_lshr_b32 s4, s2, 7
	v_writelane_b32 v254, s4, 3
	s_and_b32 s4, s16, 0x3fffffc
	v_writelane_b32 v254, s4, 4
	s_bfe_u32 s4, s2, 0x10007
	s_lshl_b32 s6, s4, 5
	v_writelane_b32 v254, s6, 5
	s_and_b32 s6, 0x80, s2
	s_cmp_eq_u32 s4, 0
	s_cselect_b64 s[42:43], -1, 0
	v_writelane_b32 v254, s42, 6
	s_cmp_lg_u32 s6, 0
	s_cselect_b64 s[6:7], -1, 0
	v_writelane_b32 v254, s43, 7
	v_writelane_b32 v254, s6, 8
	s_add_i32 s4, s9, s5
	v_writelane_b32 v255, s53, 16
	v_writelane_b32 v254, s7, 9
	v_writelane_b32 v254, s9, 10
	v_writelane_b32 v254, s4, 11
	s_add_u32 s4, s88, 0xfb400000
	v_writelane_b32 v254, s4, 12
	s_addc_u32 s4, s89, -1
	v_writelane_b32 v254, s4, 13
	s_add_u32 s4, s88, 0x103000
	v_writelane_b32 v254, s4, 14
	s_addc_u32 s4, s89, 0
	s_add_u32 s86, s88, 0x17200000
	s_addc_u32 s87, s89, 0
	s_cmp_lt_i32 s11, 0
	v_writelane_b32 v254, s4, 15
	s_cselect_b64 s[4:5], -1, 0
	v_writelane_b32 v254, s4, 16
	v_writelane_b32 v255, s54, 17
	v_readlane_b32 s62, v252, 15
	v_writelane_b32 v254, s5, 17
	s_and_b64 s[4:5], s[4:5], exec
	s_movk_i32 s4, 0xc7
	s_cselect_b32 s4, s4, 0xc6
	s_mul_i32 s4, s11, s4
	s_add_i32 s4, s4, s8
	s_mul_hi_i32 s5, s4, 0x2aaaaaab
	s_lshr_b32 s6, s5, 31
	s_ashr_i32 s5, s5, 4
	s_add_i32 s5, s5, s6
	s_mul_i32 s6, s5, 0x60
	s_lshl_b32 s7, s5, 3
	s_sub_i32 s6, s4, s6
	s_sub_i32 s4, 0x84, s7
	v_writelane_b32 v254, s8, 18
	s_min_u32 s8, s4, 8
	v_cvt_f32_ubyte0_e32 v1, s8
	v_cvt_f32_i32_e32 v0, s6
	v_rcp_iflag_f32_e32 v2, v1
	s_ashr_i32 s4, s6, 30
	s_or_b32 s9, s4, 1
	v_writelane_b32 v254, s11, 19
	v_mul_f32_e32 v2, v0, v2
	v_trunc_f32_e32 v2, v2
	v_fma_f32 v0, -v2, v1, v0
	s_lshr_b32 s4, s11, 31
	v_writelane_b32 v254, s4, 20
	v_cmp_ge_f32_e64 s[4:5], |v0|, v1
	v_cvt_i32_f32_e32 v0, v2
	s_and_b64 s[4:5], s[4:5], exec
	s_cselect_b32 s4, s9, 0
	v_writelane_b32 v255, s55, 18
	v_readfirstlane_b32 s5, v0
	s_add_i32 s4, s5, s4
	s_mul_i32 s5, s4, s8
	s_sub_i32 s5, s6, s5
	s_sext_i32_i8 s5, s5
	s_add_i32 s8, s7, s5
	s_bfe_i64 s[6:7], s[4:5], 0x80000
	s_lshl_b64 s[6:7], s[6:7], 19
	v_writelane_b32 v254, s6, 21
	s_ashr_i32 s9, s8, 31
	s_mul_i32 s5, s91, s90
	v_writelane_b32 v254, s7, 22
	s_mov_b32 s6, s8
	v_writelane_b32 v254, s6, 23
	s_mul_i32 s95, s5, s3
	s_sext_i32_i8 s3, s4
	v_writelane_b32 v254, s7, 24
	s_lshl_b64 s[6:7], s[8:9], 19
	s_add_u32 s6, s12, s6
	v_writelane_b32 v254, s12, 25
	s_addc_u32 s7, s13, s7
	s_add_u32 s4, s6, 0x40000
	v_writelane_b32 v254, s13, 26
	v_writelane_b32 v254, s3, 27
	v_writelane_b32 v254, s6, 28
	s_addc_u32 s5, s7, 0
; __device__ __forceinline__ void xcd_barrier(const XcdBarrier& b, int xtid) {
;     asm volatile("s_waitcnt vmcnt(0)" ::: "memory");
;     __syncthreads();
;     if (xtid == 0) {
;         unsigned* bar = b.bar; unsigned bx_ = b.x; asm volatile("" : "+s"(bx_));
;         __builtin_amdgcn_s_waitcnt(0);
;         unsigned nloc = b.st[0], nx = b.st[1];
;         if (nloc == 0u) { xcd_barrier_complete(bar, bx_, nloc, nx); b.st[0] = nloc; b.st[1] = nx; }
	s_abs_i32 s3, s90
	v_cvt_f32_u32_e32 v0, s3
	v_writelane_b32 v254, s7, 29
	v_writelane_b32 v254, s4, 30
	v_readlane_b32 s63, v252, 16
	v_rcp_iflag_f32_e32 v0, v0
	v_writelane_b32 v254, s5, 31
	s_sub_i32 s4, 0, s3
	v_writelane_b32 v255, s34, 19
	v_mul_f32_e32 v0, 0x4f7ffffe, v0
	v_cvt_u32_f32_e32 v0, v0
	s_mov_b64 s[62:63], s[30:31]
	v_writelane_b32 v255, s35, 20
	v_writelane_b32 v255, s62, 21
	v_readfirstlane_b32 s5, v0
	s_mul_i32 s4, s4, s5
	s_mul_hi_u32 s4, s5, s4
	s_add_i32 s5, s5, s4
	s_mul_hi_u32 s4, s5, 0x630
	s_mul_i32 s4, s4, s3
	s_sub_i32 s4, 0x630, s4
	s_sub_i32 s5, s4, s3
	s_cmp_ge_u32 s4, s3
	s_cselect_b32 s4, s5, s4
	s_sub_i32 s5, s4, s3
	s_cmp_ge_u32 s4, s3
	s_cselect_b32 s3, s5, s4
	s_cmp_ge_i32 s65, s3
	s_cselect_b64 s[4:5], -1, 0
	v_writelane_b32 v254, s4, 32
	v_writelane_b32 v255, s63, 22
	v_writelane_b32 v255, s83, 23
	v_writelane_b32 v254, s5, 33
	s_sub_i32 s4, s65, s3
	s_lshl_b32 s4, s4, 3
	s_sub_i32 s3, s90, s3
	s_add_i32 s4, s4, s16
	s_lshl_b32 s3, s3, 3
	s_cmpk_lt_u32 s4, 0x2b00
	v_writelane_b32 v254, s3, 34
	s_cselect_b64 s[6:7], -1, 0
	v_writelane_b32 v254, s6, 35
	s_add_i32 s3, s4, 0x600
	s_ashr_i32 s15, s14, 31
	v_writelane_b32 v254, s7, 36
	v_writelane_b32 v254, s3, 37
	s_abs_i32 s3, s65
	v_writelane_b32 v254, s3, 38
	s_lshl_b64 s[4:5], s[14:15], 12
	s_ashr_i32 s19, s18, 31
	v_writelane_b32 v254, s4, 39
	s_lshl_b64 s[42:43], s[18:19], 12
	s_bitset1_b32 s42, 12
	v_writelane_b32 v254, s5, 40
	v_writelane_b32 v254, s18, 41
	s_lshl_b64 s[4:5], s[18:19], 11
	s_add_u32 s3, s88, s4
	s_addc_u32 s4, s89, s5
	s_add_u32 s6, s3, 0x3800000
	v_writelane_b32 v254, s19, 42
	s_addc_u32 s7, s4, 0
	v_writelane_b32 v254, s6, 43
	s_mul_i32 s3, s10, 0x1800
	v_writelane_b32 v255, s95, 24
	v_writelane_b32 v254, s7, 44
	v_writelane_b32 v254, s14, 45
	s_lshl_b64 s[4:5], s[14:15], 11
	s_add_u32 s3, s88, s3
	v_writelane_b32 v254, s15, 46
	v_writelane_b32 v254, s4, 47
	v_writelane_b32 v255, s66, 25
	v_readlane_b32 s56, v252, 9
	v_writelane_b32 v254, s5, 48
	s_mul_hi_i32 s4, s10, 0x1800
	s_addc_u32 s4, s89, s4
	s_add_u32 s6, s3, 0xbc00000
	s_addc_u32 s7, s4, 0
	v_writelane_b32 v254, s6, 49
	s_mul_hi_i32 s5, s68, 0x1800
	s_mul_i32 s4, s68, 0x1800
	v_writelane_b32 v254, s7, 50
	s_lshr_b32 s2, s2, 2
	v_writelane_b32 v254, s4, 51
	s_and_b32 s2, s2, 48
	s_sub_i32 s2, 0, s2
	v_writelane_b32 v254, s5, 52
	v_writelane_b32 v254, s2, 53
	s_sub_i32 s2, 0, s65
	v_writelane_b32 v254, s2, 54
	v_readlane_b32 s4, v252, 17
	v_writelane_b32 v254, s28, 55
	s_sub_i32 s2, s28, 28
	v_readlane_b32 s5, v252, 18
	v_readlane_b32 s6, v252, 19
	v_readlane_b32 s7, v252, 20
	v_readlane_b32 s8, v252, 21
	v_readlane_b32 s9, v252, 22
	v_readlane_b32 s10, v252, 23
	v_readlane_b32 s11, v252, 24
	v_readlane_b32 s12, v252, 25
	v_readlane_b32 s13, v252, 26
	v_readlane_b32 s14, v252, 27
	v_readlane_b32 s15, v252, 28
	v_writelane_b32 v254, s2, 56
	s_lshl_b32 s2, s65, 6
	v_readlane_b32 s16, v252, 29
	v_readlane_b32 s17, v252, 30
	v_readlane_b32 s18, v252, 31
	v_readlane_b32 s19, v252, 32
	s_mov_b64 s[4:5], s[8:9]
	v_writelane_b32 v254, s2, 57
	s_mov_b64 s[6:7], s[10:11]
	s_mov_b64 s[8:9], s[12:13]
	s_mov_b64 s[10:11], s[14:15]
	s_mov_b64 s[12:13], s[16:17]
	s_mov_b64 s[14:15], s[18:19]
	s_add_u32 s2, s14, s42
	v_writelane_b32 v254, s42, 58
	v_writelane_b32 v255, s67, 26
	s_addc_u32 s3, s15, s43
	v_writelane_b32 v254, s43, 59
	v_writelane_b32 v255, s92, 27
	v_writelane_b32 v254, s2, 60
	v_readlane_b32 s58, v252, 11
	v_writelane_b32 v255, s93, 28
	v_writelane_b32 v254, s3, 61
	s_add_i32 s2, 0, 0x22000
	v_writelane_b32 v255, s68, 29
	v_writelane_b32 v254, s2, 62
	s_add_i32 s2, 0, 0x22004
	v_readlane_b32 s59, v252, 12
	v_readlane_b32 s60, v252, 13
	v_writelane_b32 v255, s70, 30
	v_mov_b32_e32 v248, 1
	v_mov_b32_e32 v162, 0x358637bd
	v_mov_b32_e32 v249, 0x41b17218
	s_movk_i32 s76, 0x1000
	s_movk_i32 s77, 0x1800
	s_mov_b32 s78, 0x800000
	s_movk_i32 s79, 0x7fff
	s_mov_b32 s82, 0xffff0000
	v_writelane_b32 v254, s2, 63
	s_mov_b32 s91, 0x3f317217
	s_mov_b32 s80, 0x7f800000
	s_movk_i32 s81, 0xfeff
	s_mov_b32 s3, 0x61000
	s_mov_b64 s[72:73], 0x80
	s_mov_b32 s56, s97
	s_mov_b64 s[58:59], -1
	s_movk_i32 s60, 0x1600
	v_writelane_b32 v255, s69, 31
	s_barrier
	v_readlane_b32 s57, v252, 10
	v_readlane_b32 s61, v252, 14
	v_mbcnt_lo_u32_b32 v0, -1, 0
	v_mbcnt_hi_u32_b32 v0, -1, v0
	s_waitcnt vmcnt(0)
	s_nop 0
	v_sub_u32_e32 v0, 0, v0
	v_cmp_eq_u32_e32 vcc, s94, v0
	s_barrier
	s_and_saveexec_b64 s[4:5], vcc
	s_cbranch_execz .Lgs0_113
	v_readlane_b32 s6, v254, 62
	s_mov_b32 s2, s64
	s_waitcnt vmcnt(0) expcnt(0) lgkmcnt(0)
	v_mov_b32_e32 v0, s6
	ds_read_b32 v2, v0
	v_readlane_b32 s6, v254, 63
	s_waitcnt lgkmcnt(0)
	v_cmp_ne_u32_e32 vcc, 0, v2
	v_mov_b32_e32 v0, s6
	ds_read_b32 v0, v0
	s_cbranch_vccnz .Lgs0_77
	s_mov_b32 s12, 1
	s_branch .Lgs0_65

; __device__ __forceinline__ void xcd_barrier(const XcdBarrier& b, int xtid) {
;     ...
;     __syncthreads();
; }
.Lgs0_113:
	s_or_b64 exec, exec, s[4:5]
	s_xor_b64 s[4:5], s[58:59], -1
	v_writelane_b32 v255, s4, 34
	s_waitcnt lgkmcnt(0)
	s_barrier
	v_writelane_b32 v255, s5, 35
	s_branch .LBB0_55
